# P0 streaming reads of x and the PEER tables marked nt
# speedup vs baseline: 1.0027x; 1.0027x over previous
; #define LAS __attribute__((address_space(3)))
; __global__ void __launch_bounds__(NWAVES * 64, 2) mk_fwd(Params P) {
;     ...
;         for (int rw = gw; rw < 2 * NEXP; rw += NGW) {
;             const bool isv = rw >= NEXP; const int row = isv ? rw - NEXP : rw;
;             const float* src = (isv ? P.pv : P.pu) + (size_t)row * D + 4 * lane;
;             LAS float* stg = (LAS float*)(lds + wave * 16384 + 12288);
; #pragma unroll
;             for (int q = 0; q < 4; ++q) *(LAS f32x4*)(stg + 256 * q + 4 * lane) = *(const f32x4*)(src + 256 * q);
;             float v[16]; float am = 0.f;
; #pragma unroll
;             for (int q = 0; q < 4; ++q) { f32x4 t = *(const LAS f32x4*)(stg + 16 * lane + 4 * q);
;                 if (!isv) t = t * *(const f32x4*)(P.ffn_norm + 16 * lane + 4 * q);
.LBB0_48:
	s_cmpk_lt_i32 s63, 0x4000
	s_cselect_b64 s[44:45], -1, 0
	s_add_i32 s8, s63, 0xffffc000
	s_cmpk_gt_i32 s63, 0x3fff
	s_cselect_b64 s[6:7], -1, 0
	s_and_b64 vcc, s[6:7], exec
	s_cselect_b32 s42, s8, s63
	s_cselect_b32 s8, s53, s51
	s_cselect_b32 s23, s52, s50
	s_ashr_i32 s43, s42, 31
	s_lshl_b64 s[6:7], s[42:43], 12
	s_add_u32 s6, s23, s6
	s_addc_u32 s7, s8, s7
	global_load_dwordx4 v[2:5], v36, s[6:7] nt
	global_load_dwordx4 v[6:9], v36, s[6:7] offset:1024 nt
	global_load_dwordx4 v[10:13], v36, s[6:7] offset:2048 nt
	global_load_dwordx4 v[14:17], v36, s[6:7] offset:3072 nt
	s_waitcnt vmcnt(3)
	ds_write_b128 v1, v[2:5] offset:12288
	s_waitcnt vmcnt(2)
	ds_write_b128 v1, v[6:9] offset:13312
	s_waitcnt vmcnt(1)
	ds_write_b128 v1, v[10:13] offset:14336
	s_waitcnt vmcnt(0)
	ds_write_b128 v1, v[14:17] offset:15360
	ds_read_b128 v[14:17], v37 offset:12288
	s_cbranch_vccnz .LBB0_50
	global_load_dwordx4 v[2:5], v[20:21], off
	s_waitcnt vmcnt(0) lgkmcnt(0)
	v_pk_mul_f32 v[16:17], v[16:17], v[4:5]
	v_pk_mul_f32 v[14:15], v[14:15], v[2:3]

; __device__ __forceinline__ float wave_sum(float v) { v = row16_sum(v); v = swap_add16(v, v); return swap_add32(v, v); }
; __global__ void __launch_bounds__(NWAVES * 64, 2) mk_fwd(Params P) {
;     ...
;         { f32x4 wn[4];
; #pragma unroll
;           for (int j = 0; j < 4; ++j) wn[j] = *((const f32x4*)P.attn_norm + lane + 64 * j);
;           for (int m0 = gw * 4; m0 < M; m0 += NGW * 4) {
;             f32x4 v[4][4];
; #pragma unroll
;             for (int q = 0; q < 4; ++q) { const f32x4* xr = (const f32x4*)xrow(P.xp, P.xs, m0 + q) + lane;
; #pragma unroll
;                 for (int j = 0; j < 4; ++j) v[q][j] = xr[64 * j]; }
; #pragma unroll
;             for (int q = 0; q < 4; ++q) { float s = 0.f;
; #pragma unroll
;                 for (int j = 0; j < 4; ++j) s += (v[q][j][0] * v[q][j][0] + v[q][j][1] * v[q][j][1]) + (v[q][j][2] * v[q][j][2] + v[q][j][3] * v[q][j][3]);
;                 const float rstd = 1.0f / sqrtf(wave_sum(s) * (1.0f / D) + EPS);
.LBB0_208:
	s_or_b64 exec, exec, s[8:9]
	s_cmpk_lt_i32 s12, 0x3000
	v_mov_b32_e32 v19, 0
	s_mov_b64 s[90:91], s[72:73]
	s_cbranch_scc0 .LBB0_211
	v_lshlrev_b32_e32 v1, 4, v193
	global_load_dwordx4 v[2:5], v1, s[20:21] offset:3072 nt
	global_load_dwordx4 v[6:9], v1, s[20:21] offset:2048 nt
	global_load_dwordx4 v[10:13], v1, s[20:21] offset:1024 nt
	global_load_dwordx4 v[14:17], v1, s[20:21] nt
	s_lshl_b32 s20, s12, 2
	s_lshl_b32 s22, s90, 5
	s_ashr_i32 s21, s20, 31
	s_ashr_i32 s23, s22, 31
	s_lshl_b64 s[0:1], s[20:21], 11
	s_add_u32 s0, s58, s0
	v_lshlrev_b32_e32 v18, 3, v193
	s_addc_u32 s1, s59, s1
	v_lshl_add_u64 v[18:19], s[0:1], 0, v[18:19]
	s_mov_b64 s[0:1], 0x5000000
	v_lshl_add_u64 v[82:83], v[18:19], 0, s[0:1]
	s_waitcnt lgkmcnt(0)
	s_lshl_b64 s[42:43], s[22:23], 11
	v_mov_b32_e32 v86, 0x358637bd
	s_mov_b32 s3, 0xf800000
	v_mov_b32_e32 v87, 0x260
	s_movk_i32 s12, 0x7fff
	s_mov_b32 s13, 0xffff0000
	s_movk_i32 s33, 0x1000
.LBB0_210:
	s_add_i32 s0, s20, 0xffffc000
	s_cmpk_lt_i32 s20, 0x4000
	s_cselect_b32 s1, s21, 0
	s_cselect_b32 s0, s20, s0
	s_cselect_b32 s4, s17, s19
	s_cselect_b32 s5, s16, s18
	s_lshl_b64 s[0:1], s[0:1], 12
	s_add_u32 s0, s5, s0
	s_addc_u32 s1, s4, s1
	global_load_dwordx4 v[78:81], v1, s[0:1] nt
	global_load_dwordx4 v[74:77], v1, s[0:1] offset:1024 nt
	global_load_dwordx4 v[70:73], v1, s[0:1] offset:2048 nt
	global_load_dwordx4 v[66:69], v1, s[0:1] offset:3072 nt
	s_add_u32 s0, s20, 1
	s_addc_u32 s1, s21, 0
	s_add_i32 s4, s20, 0xffffc001
	s_cmpk_lt_i32 s0, 0x4000
	s_cselect_b32 s1, s1, 0
	s_cselect_b32 s0, s0, s4
	s_cselect_b32 s4, s17, s19
	s_cselect_b32 s5, s16, s18
	s_lshl_b64 s[0:1], s[0:1], 12
	s_add_u32 s0, s5, s0
	s_addc_u32 s1, s4, s1
	global_load_dwordx4 v[62:65], v1, s[0:1] nt
	global_load_dwordx4 v[58:61], v1, s[0:1] offset:1024 nt
	global_load_dwordx4 v[54:57], v1, s[0:1] offset:2048 nt
	global_load_dwordx4 v[50:53], v1, s[0:1] offset:3072 nt
	s_add_u32 s0, s20, 2
	s_addc_u32 s1, s21, 0
	s_add_i32 s4, s20, 0xffffc002
	s_cmpk_lt_i32 s0, 0x4000
	s_cselect_b32 s1, s1, 0
	s_cselect_b32 s0, s0, s4
	s_cselect_b32 s4, s17, s19
	s_cselect_b32 s5, s16, s18
	s_lshl_b64 s[0:1], s[0:1], 12
	s_add_u32 s0, s5, s0
	s_addc_u32 s1, s4, s1
	global_load_dwordx4 v[46:49], v1, s[0:1] nt
	global_load_dwordx4 v[42:45], v1, s[0:1] offset:1024 nt
	global_load_dwordx4 v[38:41], v1, s[0:1] offset:2048 nt
	global_load_dwordx4 v[34:37], v1, s[0:1] offset:3072 nt
	s_add_u32 s0, s20, 3
	s_addc_u32 s1, s21, 0
	s_add_i32 s4, s20, 0xffffc003
	s_cmpk_lt_i32 s0, 0x4000
	s_cselect_b32 s1, s1, 0
	s_cselect_b32 s0, s0, s4
	s_cselect_b32 s4, s17, s19
	s_cselect_b32 s5, s16, s18
	s_lshl_b64 s[0:1], s[0:1], 12
	s_add_u32 s0, s5, s0
	s_addc_u32 s1, s4, s1
	global_load_dwordx4 v[30:33], v1, s[0:1] nt
	global_load_dwordx4 v[26:29], v1, s[0:1] offset:1024 nt
	global_load_dwordx4 v[22:25], v1, s[0:1] offset:2048 nt
	global_load_dwordx4 v[18:21], v1, s[0:1] offset:3072 nt
	v_add_co_u32_e32 v84, vcc, s33, v82
	s_add_u32 s20, s20, s22
	s_nop 0
	v_addc_co_u32_e32 v85, vcc, 0, v83, vcc
	s_addc_u32 s21, s21, s23
	s_cmp_gt_i32 s20, 0xbfff
	s_waitcnt vmcnt(15)
	v_mul_f32_e32 v88, v79, v79
	v_mul_f32_e32 v89, v81, v81
	s_waitcnt vmcnt(14)
	v_mul_f32_e32 v90, v75, v75
	v_mul_f32_e32 v91, v77, v77
	s_waitcnt vmcnt(13)
	v_mul_f32_e32 v92, v71, v71
	v_mul_f32_e32 v93, v73, v73
	v_fmac_f32_e32 v88, v78, v78
	v_fmac_f32_e32 v89, v80, v80
	v_fmac_f32_e32 v90, v74, v74
	v_fmac_f32_e32 v91, v76, v76
	s_waitcnt vmcnt(12)
	v_mul_f32_e32 v94, v67, v67
	v_mul_f32_e32 v95, v69, v69
	v_fmac_f32_e32 v92, v70, v70
	v_fmac_f32_e32 v93, v72, v72
	v_add_f32_e32 v88, v88, v89
	v_add_f32_e32 v89, v90, v91
	v_fmac_f32_e32 v94, v66, v66
	v_fmac_f32_e32 v95, v68, v68
	v_add_f32_e32 v90, v92, v93
	v_add_f32_e32 v88, v88, v89
	v_add_f32_e32 v91, v94, v95
	v_add_f32_e32 v88, v88, v90
	v_add_f32_e32 v88, v88, v91
	s_waitcnt vmcnt(11)
	v_mul_f32_e32 v89, v63, v63
	v_mul_f32_e32 v90, v65, v65
	v_add_f32_dpp v88, v88, v88 quad_perm:[1,0,3,2] row_mask:0xf bank_mask:0xf bound_ctrl:1
	s_waitcnt vmcnt(10)
	v_mul_f32_e32 v91, v59, v59
	v_mul_f32_e32 v92, v61, v61
	v_add_f32_dpp v88, v88, v88 quad_perm:[2,3,0,1] row_mask:0xf bank_mask:0xf bound_ctrl:1
	s_waitcnt vmcnt(9)
	v_mul_f32_e32 v93, v55, v55
	v_mul_f32_e32 v94, v57, v57
	v_add_f32_dpp v88, v88, v88 row_half_mirror row_mask:0xf bank_mask:0xf bound_ctrl:1
	v_fmac_f32_e32 v89, v62, v62
	v_fmac_f32_e32 v90, v64, v64
	v_fmac_f32_e32 v91, v58, v58
	v_fmac_f32_e32 v92, v60, v60
	s_waitcnt vmcnt(8)
	v_mul_f32_e32 v95, v51, v51
	v_mul_f32_e32 v96, v53, v53
	v_fmac_f32_e32 v93, v54, v54
	v_fmac_f32_e32 v94, v56, v56
	v_add_f32_dpp v88, v88, v88 row_mirror row_mask:0xf bank_mask:0xf bound_ctrl:1
	v_add_f32_e32 v89, v89, v90
	v_add_f32_e32 v90, v91, v92
	v_fmac_f32_e32 v95, v50, v50
	v_fmac_f32_e32 v96, v52, v52
	v_add_f32_e32 v91, v93, v94
	v_mov_b32_e32 v93, v88
	v_add_f32_e32 v89, v89, v90
	v_add_f32_e32 v92, v95, v96
	v_permlane16_swap_b32_e32 v88, v93
	v_add_f32_e32 v89, v89, v91
	v_add_f32_e32 v88, v88, v93
	v_add_f32_e32 v89, v89, v92
	v_mov_b32_e32 v90, v88
	s_nop 1
	v_permlane32_swap_b32_e32 v88, v90
	v_add_f32_dpp v89, v89, v89 quad_perm:[1,0,3,2] row_mask:0xf bank_mask:0xf bound_ctrl:1
	s_waitcnt vmcnt(7)
	v_mul_f32_e32 v91, v47, v47
	v_mul_f32_e32 v92, v49, v49
	v_add_f32_dpp v89, v89, v89 quad_perm:[2,3,0,1] row_mask:0xf bank_mask:0xf bound_ctrl:1
	s_waitcnt vmcnt(6)
	v_mul_f32_e32 v93, v43, v43
	v_mul_f32_e32 v94, v45, v45
	s_waitcnt vmcnt(5)
	v_mul_f32_e32 v95, v39, v39
	v_mul_f32_e32 v96, v41, v41
	v_add_f32_e32 v88, v88, v90
	v_add_f32_dpp v89, v89, v89 row_half_mirror row_mask:0xf bank_mask:0xf bound_ctrl:1
	v_fmac_f32_e32 v91, v46, v46
	v_fmac_f32_e32 v92, v48, v48
	v_fmac_f32_e32 v93, v42, v42
	v_fmac_f32_e32 v94, v44, v44
	s_waitcnt vmcnt(4)
; __device__ __forceinline__ float wave_sum(float v) { v = row16_sum(v); v = swap_add16(v, v); return swap_add32(v, v); }
; __global__ void __launch_bounds__(NWAVES * 64, 2) mk_fwd(Params P) {
;     ...
;             for (int q = 0; q < 4; ++q) { float s = 0.f;
; #pragma unroll
;                 for (int j = 0; j < 4; ++j) s += (v[q][j][0] * v[q][j][0] + v[q][j][1] * v[q][j][1]) + (v[q][j][2] * v[q][j][2] + v[q][j][3] * v[q][j][3]);
;                 const float rstd = 1.0f / sqrtf(wave_sum(s) * (1.0f / D) + EPS);
	v_mul_f32_e32 v97, v35, v35
	v_mul_f32_e32 v98, v37, v37
	v_fmac_f32_e32 v95, v38, v38
	v_fmac_f32_e32 v96, v40, v40
	v_fmamk_f32 v88, v88, 0x3a800000, v86
	v_add_f32_dpp v89, v89, v89 row_mirror row_mask:0xf bank_mask:0xf bound_ctrl:1
	v_add_f32_e32 v90, v91, v92
	v_add_f32_e32 v91, v93, v94
	v_fmac_f32_e32 v97, v34, v34
	v_fmac_f32_e32 v98, v36, v36
	v_add_f32_e32 v92, v95, v96
	v_mul_f32_e32 v94, 0x4f800000, v88
	v_mov_b32_e32 v95, v89
	v_add_f32_e32 v90, v90, v91
	v_cmp_gt_f32_e32 vcc, s3, v88
	v_add_f32_e32 v93, v97, v98
	v_permlane16_swap_b32_e32 v89, v95
	v_cndmask_b32_e32 v88, v88, v94, vcc
	v_add_f32_e32 v90, v90, v92
	v_sqrt_f32_e32 v91, v88
	v_add_f32_e32 v89, v89, v95
	v_add_f32_e32 v90, v90, v93
	v_mov_b32_e32 v92, v89
	s_nop 1
	v_permlane32_swap_b32_e32 v89, v92
	v_add_f32_dpp v90, v90, v90 quad_perm:[1,0,3,2] row_mask:0xf bank_mask:0xf bound_ctrl:1
	s_waitcnt vmcnt(3)
	v_mul_f32_e32 v93, v31, v31
	v_mul_f32_e32 v94, v33, v33
	v_add_f32_dpp v90, v90, v90 quad_perm:[2,3,0,1] row_mask:0xf bank_mask:0xf bound_ctrl:1
	s_waitcnt vmcnt(2)
	v_mul_f32_e32 v95, v27, v27
	v_mul_f32_e32 v96, v29, v29
	s_waitcnt vmcnt(1)
	v_mul_f32_e32 v97, v23, v23
	v_mul_f32_e32 v98, v25, v25
	s_waitcnt vmcnt(0)
	v_mul_f32_e32 v99, v19, v19
	v_mul_f32_e32 v100, v21, v21
	v_add_f32_e32 v89, v89, v92
	v_add_f32_dpp v90, v90, v90 row_half_mirror row_mask:0xf bank_mask:0xf bound_ctrl:1
	v_fmac_f32_e32 v93, v30, v30
	v_fmac_f32_e32 v94, v32, v32
	v_fmac_f32_e32 v95, v26, v26
	v_fmac_f32_e32 v96, v28, v28
	v_fmac_f32_e32 v97, v22, v22
	v_fmac_f32_e32 v98, v24, v24
	v_fmac_f32_e32 v99, v18, v18
	v_fmac_f32_e32 v100, v20, v20
	v_add_u32_e32 v92, -1, v91
	v_fmamk_f32 v89, v89, 0x3a800000, v86
	v_add_f32_dpp v90, v90, v90 row_mirror row_mask:0xf bank_mask:0xf bound_ctrl:1
	v_add_u32_e32 v101, 1, v91
	v_add_f32_e32 v93, v93, v94
	v_add_f32_e32 v94, v95, v96
	v_add_f32_e32 v95, v97, v98
	v_add_f32_e32 v96, v99, v100
	v_fma_f32 v97, -v92, v91, v88
	v_mul_f32_e32 v99, 0x4f800000, v89
	v_cmp_gt_f32_e64 s[0:1], s3, v89
	v_mov_b32_e32 v100, v90
	v_fma_f32 v98, -v101, v91, v88
	v_add_f32_e32 v93, v93, v94
	v_cmp_ge_f32_e64 s[4:5], 0, v97
	v_cndmask_b32_e64 v89, v89, v99, s[0:1]
	v_permlane16_swap_b32_e32 v90, v100
	v_cndmask_b32_e64 v91, v91, v92, s[4:5]
	v_add_f32_e32 v92, v93, v95
	v_cmp_lt_f32_e64 s[4:5], 0, v98
	v_sqrt_f32_e32 v93, v89
	v_add_f32_e32 v90, v90, v100
	v_cndmask_b32_e64 v91, v91, v101, s[4:5]
	v_add_f32_e32 v92, v92, v96
	v_mov_b32_e32 v95, v90
	v_mul_f32_e32 v94, 0x37800000, v91
	v_add_f32_dpp v92, v92, v92 quad_perm:[1,0,3,2] row_mask:0xf bank_mask:0xf bound_ctrl:1
	v_permlane32_swap_b32_e32 v90, v95
	v_cndmask_b32_e32 v91, v91, v94, vcc
	v_add_f32_dpp v92, v92, v92 quad_perm:[2,3,0,1] row_mask:0xf bank_mask:0xf bound_ctrl:1
	v_cmp_class_f32_e32 vcc, v88, v87
	v_add_f32_e32 v90, v90, v95
	v_add_u32_e32 v95, -1, v93
	v_cndmask_b32_e32 v88, v91, v88, vcc
	v_add_f32_dpp v91, v92, v92 row_half_mirror row_mask:0xf bank_mask:0xf bound_ctrl:1
	v_fmamk_f32 v90, v90, 0x3a800000, v86
	v_div_scale_f32 v92, s[4:5], v88, v88, 1.0
	v_add_u32_e32 v96, 1, v93
	v_add_f32_dpp v91, v91, v91 row_mirror row_mask:0xf bank_mask:0xf bound_ctrl:1
	v_fma_f32 v98, -v95, v93, v89
	v_mul_f32_e32 v100, 0x4f800000, v90
	v_cmp_gt_f32_e64 s[8:9], s3, v90
	v_rcp_f32_e32 v97, v92
	v_fma_f32 v99, -v96, v93, v89
	v_mov_b32_e32 v101, v91
	v_cmp_ge_f32_e64 s[4:5], 0, v98
	v_cndmask_b32_e64 v90, v90, v100, s[8:9]
	v_permlane16_swap_b32_e32 v91, v101
	v_cndmask_b32_e64 v93, v93, v95, s[4:5]
	v_cmp_lt_f32_e64 s[4:5], 0, v99
	v_sqrt_f32_e32 v95, v90
	v_add_f32_e32 v91, v91, v101
	v_cndmask_b32_e64 v93, v93, v96, s[4:5]
	v_mul_f32_e32 v96, 0x37800000, v93
	v_mov_b32_e32 v98, v91
	v_fma_f32 v99, -v92, v97, 1.0
	v_cndmask_b32_e64 v93, v93, v96, s[0:1]
	v_cmp_class_f32_e64 s[0:1], v89, v87
	v_permlane32_swap_b32_e32 v91, v98
	v_div_scale_f32 v94, vcc, 1.0, v88, 1.0
	v_fmac_f32_e32 v97, v99, v97
	v_cndmask_b32_e64 v89, v93, v89, s[0:1]
	v_add_f32_e32 v91, v91, v98
	v_add_u32_e32 v99, -1, v95
	v_mul_f32_e32 v93, v94, v97
	v_div_scale_f32 v96, s[0:1], v89, v89, 1.0
	v_add_u32_e32 v100, 1, v95
	v_fmamk_f32 v91, v91, 0x3a800000, v86
	v_fma_f32 v103, -v99, v95, v90
	v_fma_f32 v101, -v92, v93, v94
	v_fma_f32 v104, -v100, v95, v90
	v_mul_f32_e32 v105, 0x4f800000, v91
	v_cmp_gt_f32_e64 s[6:7], s3, v91
	v_cmp_ge_f32_e64 s[0:1], 0, v103
	v_rcp_f32_e32 v102, v96
	v_fmac_f32_e32 v93, v101, v97
	v_cndmask_b32_e64 v95, v95, v99, s[0:1]
	v_cmp_lt_f32_e64 s[0:1], 0, v104
	v_cndmask_b32_e64 v91, v91, v105, s[6:7]
	v_fma_f32 v92, -v92, v93, v94
	v_cndmask_b32_e64 v94, v95, v100, s[0:1]
	v_sqrt_f32_e32 v95, v91
	v_div_fmas_f32 v92, v92, v97, v93
	v_mul_f32_e32 v93, 0x37800000, v94
	v_div_fixup_f32 v88, v92, v88, 1.0
	v_fma_f32 v92, -v96, v102, 1.0
	v_cndmask_b32_e64 v93, v94, v93, s[8:9]
	v_cmp_class_f32_e32 vcc, v90, v87
	v_div_scale_f32 v98, s[4:5], 1.0, v89, 1.0
	v_mul_f32_e32 v78, v88, v78
	v_mul_f32_e32 v79, v88, v79
	v_mul_f32_e32 v80, v88, v80
	v_mul_f32_e32 v81, v88, v81
	v_mul_f32_e32 v74, v88, v74
	v_mul_f32_e32 v75, v88, v75
	v_mul_f32_e32 v76, v88, v76
	v_mul_f32_e32 v77, v88, v77
	v_mul_f32_e32 v70, v88, v70
	v_mul_f32_e32 v71, v88, v71
	v_mul_f32_e32 v72, v88, v72
	v_mul_f32_e32 v73, v88, v73
	v_mul_f32_e32 v66, v88, v66
	v_mul_f32_e32 v67, v88, v67
	v_mul_f32_e32 v68, v88, v68
	v_mul_f32_e32 v69, v88, v69
	v_fmac_f32_e32 v102, v92, v102
	v_cndmask_b32_e32 v88, v93, v90, vcc
	v_add_u32_e32 v94, -1, v95
	v_mul_f32_e32 v78, v78, v14
	v_mul_f32_e32 v80, v80, v16
	v_mul_f32_e32 v74, v74, v10
	v_mul_f32_e32 v67, v67, v3
	v_mul_f32_e32 v68, v68, v4
	v_mul_f32_e32 v90, v98, v102
	v_div_scale_f32 v92, s[0:1], v88, v88, 1.0
; __device__ __forceinline__ unsigned f2bf(float f) { unsigned u = __builtin_bit_cast(unsigned, f); return (u + 0x7fffu + ((u >> 16) & 1u)) >> 16; }
; __device__ __forceinline__ unsigned pk2(float lo, float hi) { return f2bf(lo) | (f2bf(hi) << 16); }
; __global__ void __launch_bounds__(NWAVES * 64, 2) mk_fwd(Params P) {
;     ...
;                 unsigned long long* o8 = (unsigned long long*)(XN + (size_t)(m0 + q) * D) + lane;
; #pragma unroll
;                 for (int j = 0; j < 4; ++j) o8[64 * j] = (unsigned long long)pk2(v[q][j][0] * rstd * wn[j][0], v[q][j][1] * rstd * wn[j][1]) | ((unsigned long long)pk2(v[q][j][2] * rstd * wn[j][2], v[q][j][3] * rstd * wn[j][3]) << 32); }
	v_add_u32_e32 v97, 1, v95
	v_fma_f32 v118, -v94, v95, v91
	v_mul_f32_e32 v79, v79, v15
	v_mul_f32_e32 v81, v81, v17
	v_mul_f32_e32 v75, v75, v11
	v_mul_f32_e32 v76, v76, v12
	v_mul_f32_e32 v70, v70, v6
	v_mul_f32_e32 v72, v72, v8
	v_mul_f32_e32 v66, v66, v2
	v_mul_f32_e32 v69, v69, v5
	v_bfe_u32 v99, v78, 16, 1
	v_bfe_u32 v101, v80, 16, 1
	v_bfe_u32 v104, v74, 16, 1
	v_bfe_u32 v113, v67, 16, 1
	v_bfe_u32 v114, v68, 16, 1
	v_fma_f32 v116, -v96, v90, v98
	v_rcp_f32_e32 v117, v92
	v_fma_f32 v119, -v97, v95, v91
	v_cmp_ge_f32_e32 vcc, 0, v118
	v_mul_f32_e32 v77, v77, v13
	v_mul_f32_e32 v71, v71, v7
	v_mul_f32_e32 v73, v73, v9
	v_bfe_u32 v100, v79, 16, 1
	v_bfe_u32 v103, v81, 16, 1
	v_bfe_u32 v105, v75, 16, 1
	v_bfe_u32 v106, v76, 16, 1
	v_bfe_u32 v108, v70, 16, 1
	v_bfe_u32 v110, v72, 16, 1
	v_bfe_u32 v112, v66, 16, 1
	v_bfe_u32 v115, v69, 16, 1
	v_add3_u32 v78, v78, v99, s12
	v_add3_u32 v80, v80, v101, s12
	v_add3_u32 v74, v74, v104, s12
	v_add3_u32 v99, v67, v113, s12
	v_add3_u32 v67, v68, v114, s12
	v_fmac_f32_e32 v90, v116, v102
	v_cndmask_b32_e32 v68, v95, v94, vcc
	v_cmp_lt_f32_e32 vcc, 0, v119
	v_bfe_u32 v107, v77, 16, 1
	v_bfe_u32 v109, v71, 16, 1
	v_bfe_u32 v111, v73, 16, 1
	v_add3_u32 v79, v79, v100, s12
	v_add3_u32 v81, v81, v103, s12
	v_add3_u32 v75, v75, v105, s12
	v_add3_u32 v76, v76, v106, s12
	v_add3_u32 v70, v70, v108, s12
	v_add3_u32 v72, v72, v110, s12
	v_add3_u32 v66, v66, v112, s12
	v_add3_u32 v100, v69, v115, s12
	v_lshrrev_b32_e32 v69, 16, v78
	v_lshrrev_b32_e32 v78, 16, v80
	v_lshrrev_b32_e32 v74, 16, v74
	v_fma_f32 v95, -v96, v90, v98
	v_cndmask_b32_e32 v96, v68, v97, vcc
	s_mov_b64 vcc, s[4:5]
	v_add3_u32 v77, v77, v107, s12
	v_add3_u32 v71, v71, v109, s12
	v_add3_u32 v73, v73, v111, s12
	v_lshrrev_b32_e32 v76, 16, v76
	v_lshrrev_b32_e32 v70, 16, v70
	v_lshrrev_b32_e32 v72, 16, v72
	v_lshrrev_b32_e32 v80, 16, v66
	v_lshrrev_b32_e32 v94, 16, v67
	v_and_or_b32 v66, v79, s13, v69
	v_and_or_b32 v67, v81, s13, v78
	v_and_or_b32 v68, v75, s13, v74
	v_div_fmas_f32 v74, v95, v102, v90
	v_mul_f32_e32 v75, 0x37800000, v96
	v_and_or_b32 v69, v77, s13, v76
	v_and_or_b32 v70, v71, s13, v70
	v_and_or_b32 v71, v73, s13, v72
	v_and_or_b32 v72, v99, s13, v80
	v_and_or_b32 v73, v100, s13, v94
	global_store_dwordx2 v[82:83], v[66:67], off
	global_store_dwordx2 v[82:83], v[68:69], off offset:512
	global_store_dwordx2 v[82:83], v[70:71], off offset:1024
	global_store_dwordx2 v[82:83], v[72:73], off offset:1536
	v_div_fixup_f32 v66, v74, v89, 1.0
	v_fma_f32 v67, -v92, v117, 1.0
	v_cndmask_b32_e64 v68, v96, v75, s[6:7]
	v_cmp_class_f32_e32 vcc, v91, v87
	v_div_scale_f32 v93, s[0:1], 1.0, v88, 1.0
	v_mul_f32_e32 v62, v66, v62
	v_mul_f32_e32 v63, v66, v63
	v_mul_f32_e32 v64, v66, v64
	v_mul_f32_e32 v65, v66, v65
	v_mul_f32_e32 v58, v66, v58
	v_mul_f32_e32 v59, v66, v59
	v_mul_f32_e32 v60, v66, v60
	v_mul_f32_e32 v61, v66, v61
	v_mul_f32_e32 v54, v66, v54
	v_mul_f32_e32 v55, v66, v55
	v_mul_f32_e32 v56, v66, v56
	v_mul_f32_e32 v57, v66, v57
	v_mul_f32_e32 v50, v66, v50
	v_mul_f32_e32 v51, v66, v51
	v_mul_f32_e32 v52, v66, v52
	v_mul_f32_e32 v53, v66, v53
	v_fmac_f32_e32 v117, v67, v117
	v_cndmask_b32_e32 v66, v68, v91, vcc
	v_mul_f32_e32 v62, v62, v14
	v_mul_f32_e32 v64, v64, v16
	v_mul_f32_e32 v58, v58, v10
	v_mul_f32_e32 v67, v93, v117
	v_div_scale_f32 v68, s[4:5], v66, v66, 1.0
	v_mul_f32_e32 v63, v63, v15
	v_mul_f32_e32 v65, v65, v17
	v_mul_f32_e32 v59, v59, v11
	v_mul_f32_e32 v60, v60, v12
	v_mul_f32_e32 v54, v54, v6
	v_mul_f32_e32 v56, v56, v8
	v_mul_f32_e32 v50, v50, v2
	v_mul_f32_e32 v51, v51, v3
	v_mul_f32_e32 v52, v52, v4
	v_mul_f32_e32 v53, v53, v5
	v_bfe_u32 v70, v62, 16, 1
	v_bfe_u32 v72, v64, 16, 1
	v_bfe_u32 v74, v58, 16, 1
	v_fma_f32 v95, -v92, v67, v93
	v_rcp_f32_e32 v96, v68
	v_mul_f32_e32 v61, v61, v13
	v_mul_f32_e32 v55, v55, v7
	v_mul_f32_e32 v57, v57, v9
	v_bfe_u32 v71, v63, 16, 1
	v_bfe_u32 v73, v65, 16, 1
	v_bfe_u32 v75, v59, 16, 1
	v_bfe_u32 v76, v60, 16, 1
	v_bfe_u32 v78, v54, 16, 1
	v_bfe_u32 v80, v56, 16, 1
	v_bfe_u32 v89, v50, 16, 1
	v_bfe_u32 v90, v51, 16, 1
	v_bfe_u32 v91, v52, 16, 1
	v_bfe_u32 v94, v53, 16, 1
	v_add3_u32 v62, v62, v70, s12
	v_add3_u32 v64, v64, v72, s12
	v_add3_u32 v58, v58, v74, s12
	v_fmac_f32_e32 v67, v95, v117
	v_bfe_u32 v77, v61, 16, 1
	v_bfe_u32 v79, v55, 16, 1
	v_bfe_u32 v81, v57, 16, 1
	v_add3_u32 v63, v63, v71, s12
	v_add3_u32 v65, v65, v73, s12
	v_add3_u32 v59, v59, v75, s12
	v_add3_u32 v60, v60, v76, s12
	v_add3_u32 v54, v54, v78, s12
	v_add3_u32 v56, v56, v80, s12
	v_add3_u32 v50, v50, v89, s12
	v_add3_u32 v70, v51, v90, s12
	v_add3_u32 v51, v52, v91, s12
	v_add3_u32 v71, v53, v94, s12
	v_lshrrev_b32_e32 v52, 16, v62
	v_lshrrev_b32_e32 v53, 16, v64
	v_lshrrev_b32_e32 v58, 16, v58
	v_fma_f32 v72, -v92, v67, v93
	s_mov_b64 vcc, s[0:1]
	v_add3_u32 v61, v61, v77, s12
	v_add3_u32 v55, v55, v79, s12
	v_add3_u32 v57, v57, v81, s12
	v_lshrrev_b32_e32 v60, 16, v60
	v_lshrrev_b32_e32 v54, 16, v54
	v_lshrrev_b32_e32 v56, 16, v56
	v_lshrrev_b32_e32 v62, 16, v50
	v_lshrrev_b32_e32 v64, 16, v51
	v_and_or_b32 v50, v63, s13, v52
	v_and_or_b32 v51, v65, s13, v53
	v_and_or_b32 v52, v59, s13, v58
	v_div_fmas_f32 v58, v72, v117, v67
	v_and_or_b32 v53, v61, s13, v60
	v_and_or_b32 v54, v55, s13, v54
	v_and_or_b32 v55, v57, s13, v56
	v_and_or_b32 v56, v70, s13, v62
	v_and_or_b32 v57, v71, s13, v64
	global_store_dwordx2 v[82:83], v[50:51], off offset:2048
	global_store_dwordx2 v[82:83], v[52:53], off offset:2560
	global_store_dwordx2 v[82:83], v[54:55], off offset:3072
	global_store_dwordx2 v[82:83], v[56:57], off offset:3584
	v_div_fixup_f32 v50, v58, v88, 1.0
; __device__ __forceinline__ float wave_sum(float v) { v = row16_sum(v); v = swap_add16(v, v); return swap_add32(v, v); }
; __device__ __forceinline__ unsigned pk2(float lo, float hi) { return f2bf(lo) | (f2bf(hi) << 16); }
; __global__ void __launch_bounds__(NWAVES * 64, 2) mk_fwd(Params P) {
;     ...
;           for (int m0 = gw * 4; m0 < M; m0 += NGW * 4) {
;             f32x4 v[4][4];
; #pragma unroll
;             for (int q = 0; q < 4; ++q) { const f32x4* xr = (const f32x4*)xrow(P.xp, P.xs, m0 + q) + lane;
; #pragma unroll
;                 for (int j = 0; j < 4; ++j) v[q][j] = xr[64 * j]; }
; #pragma unroll
;             for (int q = 0; q < 4; ++q) { float s = 0.f;
; #pragma unroll
;                 for (int j = 0; j < 4; ++j) s += (v[q][j][0] * v[q][j][0] + v[q][j][1] * v[q][j][1]) + (v[q][j][2] * v[q][j][2] + v[q][j][3] * v[q][j][3]);
;                 const float rstd = 1.0f / sqrtf(wave_sum(s) * (1.0f / D) + EPS);
;                 unsigned long long* o8 = (unsigned long long*)(XN + (size_t)(m0 + q) * D) + lane;
; #pragma unroll
;                 for (int j = 0; j < 4; ++j) o8[64 * j] = (unsigned long long)pk2(v[q][j][0] * rstd * wn[j][0], v[q][j][1] * rstd * wn[j][1]) | ((unsigned long long)pk2(v[q][j][2] * rstd * wn[j][2], v[q][j][3] * rstd * wn[j][3]) << 32); }
	v_fma_f32 v51, -v68, v96, 1.0
	v_div_scale_f32 v69, s[4:5], 1.0, v66, 1.0
	v_mul_f32_e32 v46, v50, v46
	v_mul_f32_e32 v48, v50, v48
	v_mul_f32_e32 v42, v50, v42
	v_fmac_f32_e32 v96, v51, v96
	v_mul_f32_e32 v47, v50, v47
	v_mul_f32_e32 v49, v50, v49
	v_mul_f32_e32 v43, v50, v43
	v_mul_f32_e32 v44, v50, v44
	v_mul_f32_e32 v45, v50, v45
	v_mul_f32_e32 v38, v50, v38
	v_mul_f32_e32 v39, v50, v39
	v_mul_f32_e32 v40, v50, v40
	v_mul_f32_e32 v41, v50, v41
	v_mul_f32_e32 v34, v50, v34
	v_mul_f32_e32 v35, v50, v35
	v_mul_f32_e32 v36, v50, v36
	v_mul_f32_e32 v37, v50, v37
	v_mul_f32_e32 v46, v46, v14
	v_mul_f32_e32 v48, v48, v16
	v_mul_f32_e32 v42, v42, v10
	v_mul_f32_e32 v50, v69, v96
	v_mul_f32_e32 v47, v47, v15
	v_mul_f32_e32 v49, v49, v17
	v_mul_f32_e32 v43, v43, v11
	v_mul_f32_e32 v44, v44, v12
	v_mul_f32_e32 v38, v38, v6
	v_mul_f32_e32 v40, v40, v8
	v_mul_f32_e32 v34, v34, v2
	v_mul_f32_e32 v35, v35, v3
	v_mul_f32_e32 v36, v36, v4
	v_mul_f32_e32 v37, v37, v5
	v_bfe_u32 v51, v46, 16, 1
	v_bfe_u32 v53, v48, 16, 1
	v_bfe_u32 v55, v42, 16, 1
	v_fma_f32 v70, -v68, v50, v69
	v_mul_f32_e32 v45, v45, v13
	v_mul_f32_e32 v39, v39, v7
	v_mul_f32_e32 v41, v41, v9
	v_bfe_u32 v52, v47, 16, 1
	v_bfe_u32 v54, v49, 16, 1
	v_bfe_u32 v56, v43, 16, 1
	v_bfe_u32 v57, v44, 16, 1
	v_bfe_u32 v59, v38, 16, 1
	v_bfe_u32 v61, v40, 16, 1
	v_bfe_u32 v63, v34, 16, 1
	v_bfe_u32 v64, v35, 16, 1
	v_bfe_u32 v65, v36, 16, 1
	v_bfe_u32 v67, v37, 16, 1
	v_add3_u32 v46, v46, v51, s12
	v_add3_u32 v48, v48, v53, s12
	v_add3_u32 v42, v42, v55, s12
	v_fmac_f32_e32 v50, v70, v96
	v_bfe_u32 v58, v45, 16, 1
	v_bfe_u32 v60, v39, 16, 1
	v_bfe_u32 v62, v41, 16, 1
	v_add3_u32 v47, v47, v52, s12
	v_add3_u32 v49, v49, v54, s12
	v_add3_u32 v43, v43, v56, s12
	v_add3_u32 v44, v44, v57, s12
	v_add3_u32 v38, v38, v59, s12
	v_add3_u32 v40, v40, v61, s12
	v_add3_u32 v34, v34, v63, s12
	v_add3_u32 v51, v35, v64, s12
	v_add3_u32 v35, v36, v65, s12
	v_add3_u32 v52, v37, v67, s12
	v_lshrrev_b32_e32 v36, 16, v46
	v_lshrrev_b32_e32 v37, 16, v48
	v_lshrrev_b32_e32 v42, 16, v42
	v_fma_f32 v53, -v68, v50, v69
	s_mov_b64 vcc, s[4:5]
	v_add3_u32 v45, v45, v58, s12
	v_add3_u32 v39, v39, v60, s12
	v_add3_u32 v41, v41, v62, s12
	v_lshrrev_b32_e32 v44, 16, v44
	v_lshrrev_b32_e32 v38, 16, v38
	v_lshrrev_b32_e32 v40, 16, v40
	v_lshrrev_b32_e32 v46, 16, v34
	v_lshrrev_b32_e32 v48, 16, v35
	v_and_or_b32 v34, v47, s13, v36
	v_and_or_b32 v35, v49, s13, v37
	v_and_or_b32 v36, v43, s13, v42
	v_div_fmas_f32 v42, v53, v96, v50
	v_and_or_b32 v37, v45, s13, v44
	v_and_or_b32 v38, v39, s13, v38
	v_and_or_b32 v39, v41, s13, v40
	v_and_or_b32 v40, v51, s13, v46
	v_and_or_b32 v41, v52, s13, v48
	global_store_dwordx2 v[84:85], v[34:35], off
	global_store_dwordx2 v[84:85], v[36:37], off offset:512
	global_store_dwordx2 v[84:85], v[38:39], off offset:1024
	global_store_dwordx2 v[84:85], v[40:41], off offset:1536
	v_div_fixup_f32 v34, v42, v66, 1.0
	v_mul_f32_e32 v30, v34, v30
	v_mul_f32_e32 v32, v34, v32
	v_mul_f32_e32 v31, v34, v31
	v_mul_f32_e32 v33, v34, v33
	v_mul_f32_e32 v26, v34, v26
	v_mul_f32_e32 v28, v34, v28
	v_mul_f32_e32 v22, v34, v22
	v_mul_f32_e32 v24, v34, v24
	v_mul_f32_e32 v18, v34, v18
	v_mul_f32_e32 v19, v34, v19
	v_mul_f32_e32 v20, v34, v20
	v_mul_f32_e32 v21, v34, v21
	v_mul_f32_e32 v30, v30, v14
	v_mul_f32_e32 v32, v32, v16
	v_mul_f32_e32 v27, v34, v27
	v_mul_f32_e32 v29, v34, v29
	v_mul_f32_e32 v23, v34, v23
	v_mul_f32_e32 v25, v34, v25
	v_mul_f32_e32 v31, v31, v15
	v_mul_f32_e32 v33, v33, v17
	v_mul_f32_e32 v26, v26, v10
	v_mul_f32_e32 v28, v28, v12
	v_mul_f32_e32 v22, v22, v6
	v_mul_f32_e32 v24, v24, v8
	v_mul_f32_e32 v18, v18, v2
	v_mul_f32_e32 v19, v19, v3
	v_mul_f32_e32 v20, v20, v4
	v_mul_f32_e32 v21, v21, v5
	v_bfe_u32 v34, v30, 16, 1
	v_bfe_u32 v36, v32, 16, 1
	v_mul_f32_e32 v27, v27, v11
	v_mul_f32_e32 v29, v29, v13
	v_mul_f32_e32 v23, v23, v7
	v_mul_f32_e32 v25, v25, v9
	v_bfe_u32 v35, v31, 16, 1
	v_bfe_u32 v37, v33, 16, 1
	v_bfe_u32 v38, v26, 16, 1
	v_bfe_u32 v40, v28, 16, 1
	v_bfe_u32 v42, v22, 16, 1
	v_bfe_u32 v44, v24, 16, 1
	v_bfe_u32 v46, v18, 16, 1
	v_bfe_u32 v47, v19, 16, 1
	v_bfe_u32 v48, v20, 16, 1
	v_bfe_u32 v49, v21, 16, 1
	v_add3_u32 v30, v30, v34, s12
	v_add3_u32 v32, v32, v36, s12
	v_bfe_u32 v39, v27, 16, 1
	v_bfe_u32 v41, v29, 16, 1
	v_bfe_u32 v43, v23, 16, 1
	v_bfe_u32 v45, v25, 16, 1
	v_add3_u32 v31, v31, v35, s12
	v_add3_u32 v33, v33, v37, s12
	v_add3_u32 v26, v26, v38, s12
	v_add3_u32 v28, v28, v40, s12
	v_add3_u32 v22, v22, v42, s12
	v_add3_u32 v24, v24, v44, s12
	v_add3_u32 v18, v18, v46, s12
	v_add3_u32 v34, v19, v47, s12
	v_add3_u32 v19, v20, v48, s12
	v_add3_u32 v35, v21, v49, s12
	v_lshrrev_b32_e32 v20, 16, v30
	v_lshrrev_b32_e32 v21, 16, v32
	v_lshl_add_u64 v[82:83], v[82:83], 0, s[42:43]
	v_add3_u32 v27, v27, v39, s12
	v_add3_u32 v29, v29, v41, s12
	v_add3_u32 v23, v23, v43, s12
	v_add3_u32 v25, v25, v45, s12
	v_lshrrev_b32_e32 v26, 16, v26
	v_lshrrev_b32_e32 v28, 16, v28
	v_lshrrev_b32_e32 v22, 16, v22
	v_lshrrev_b32_e32 v24, 16, v24
	v_lshrrev_b32_e32 v30, 16, v18
	v_lshrrev_b32_e32 v32, 16, v19
	v_and_or_b32 v18, v31, s13, v20
	v_and_or_b32 v19, v33, s13, v21
	v_and_or_b32 v20, v27, s13, v26
	v_and_or_b32 v21, v29, s13, v28
	v_and_or_b32 v22, v23, s13, v22
	v_and_or_b32 v23, v25, s13, v24
	v_and_or_b32 v24, v34, s13, v30
	v_and_or_b32 v25, v35, s13, v32
	global_store_dwordx2 v[84:85], v[18:19], off offset:2048
	global_store_dwordx2 v[84:85], v[20:21], off offset:2560
	global_store_dwordx2 v[84:85], v[22:23], off offset:3072
	global_store_dwordx2 v[84:85], v[24:25], off offset:3584
	s_cbranch_scc0 .LBB0_210
